# FFN-up K-loop: LDS-DMA staging loads use scalar base + 32-bit lane offset (no per-load 64-bit VALU address add)
# speedup vs baseline: 1.0269x; 1.0013x over previous
; #define PG8_STAGE(bufoff, gbase, voff) do { _Pragma("unroll") for (int _i = 0; _i < 2; ++_i) \
;         __builtin_amdgcn_global_load_lds((const unsigned*)((const char*)(gbase) + (voff)[_i]), (LAS unsigned*)(lds + (bufoff) + ldsw + _i * 8192), 16, 0, 0); } while (0)
; #define PG8_LDA(dst, b, h) do { _Pragma("unroll") for (int m = 0; m < 4; ++m) _Pragma("unroll") for (int k = 0; k < 2; ++k) dst[m][k] = *(const LAS bf16x8*)(lds + PG8_SA(b, h) + aoff + m * 2048 + k * 1024); } while (0)
; #define PG8_LDB(dst, b, h) do { _Pragma("unroll") for (int n = 0; n < 2; ++n) _Pragma("unroll") for (int k = 0; k < 2; ++k) dst[n][k] = *(const LAS bf16x8*)(lds + PG8_SB(b, h) + boff + n * 2048 + k * 1024); } while (0)
; #define PG8_MMA(ai, bj, At, Bt) do { __builtin_amdgcn_s_setprio(1); _Pragma("unroll") for (int m = 0; m < 4; ++m) _Pragma("unroll") for (int n = 0; n < 2; ++n) _Pragma("unroll") for (int k = 0; k < 2; ++k) \
;         acc[ai][bj][m][n] = __builtin_amdgcn_mfma_f32_16x16x32_bf16(Bt[n][k], At[m][k], acc[ai][bj][m][n], 0, 0, 0); __builtin_amdgcn_s_setprio(0); } while (0)
; #define PG8_WAIT_V(n) asm volatile("s_waitcnt vmcnt(" #n ")" ::: "memory")
; #define PG8_WAIT_L(n) asm volatile("s_waitcnt lgkmcnt(" #n ")" ::: "memory")
; #define PG8_BAR __builtin_amdgcn_s_barrier()
; #define PG8_SCHED __builtin_amdgcn_sched_barrier(0)
; template <class Epi, class Sched>
; __device__ __forceinline__ void gemm_phase(LAS unsigned char* lds, const int K, const Sched& S, const Epi& E) {
;     ...
;             PG8_LDB(B0, 0, 0); PG8_SCHED; PG8_LDA(At, 0, 0); PG8_STAGE(PG8_SA(1, 1), a1 + hstepA, voffA);
;             PG8_WAIT_L(8); PG8_BAR; PG8_WAIT_L(0); PG8_MMA(0, 0, At, B0); PG8_BAR; PG8_SCHED;
;             PG8_LDB(B1, 0, 1); PG8_STAGE(PG8_SB(0, 0), b2, voffB);
;             PG8_BAR; PG8_WAIT_L(0); PG8_MMA(0, 1, At, B1); PG8_BAR;
;             PG8_LDA(At, 0, 1); PG8_STAGE(PG8_SA(0, 0), a2, voffA);
;             PG8_BAR; PG8_WAIT_L(0); PG8_MMA(1, 0, At, B0); PG8_BAR; PG8_SCHED;
;             PG8_STAGE(PG8_SB(0, 1), b2 + hstep, voffB);
;             PG8_WAIT_V(6); PG8_BAR; PG8_MMA(1, 1, At, B1); PG8_BAR;
.Lpeel_p7:
	ds_read_b128 v[128:131], v158
	ds_read_b128 v[132:135], v158 offset:1024
	ds_read_b128 v[148:151], v158 offset:2048
	ds_read_b128 v[162:165], v158 offset:3072
	s_add_u32 s68, s12, 0x100
	s_addc_u32 s69, s13, 0
	s_cmp_eq_u32 s49, 12
	s_cselect_b32 s73, s63, s69
	s_cselect_b32 s72, s62, s68
	s_cselect_b32 s71, s65, s33
	s_cselect_b32 s70, s64, s11
	s_add_i32 m0, s67, 0xc000
	ds_read_b128 v[166:169], v159
	ds_read_b128 v[172:175], v159 offset:1024
	ds_read_b128 v[176:179], v159 offset:2048
	ds_read_b128 v[180:183], v159 offset:3072
	ds_read_b128 v[184:187], v159 offset:4096
	ds_read_b128 v[188:191], v159 offset:5120
	ds_read_b128 v[192:195], v159 offset:6144
	ds_read_b128 v[196:199], v159 offset:7168
	global_load_lds_dwordx4 v144, s[12:13]
	s_add_i32 m0, s67, 0xe000
	s_nop 0
	global_load_lds_dwordx4 v146, s[12:13]
	s_waitcnt lgkmcnt(8)
	s_barrier
	s_waitcnt lgkmcnt(0)
	s_setprio 1
	s_waitcnt lgkmcnt(0)
	v_mfma_f32_16x16x32_bf16 v[84:87], v[128:131], v[166:169], 0
	v_mfma_f32_16x16x32_bf16 v[76:79], v[148:151], v[166:169], 0
	v_mfma_f32_16x16x32_bf16 v[124:127], v[128:131], v[176:179], 0
	v_mfma_f32_16x16x32_bf16 v[72:75], v[148:151], v[176:179], 0
	v_mfma_f32_16x16x32_bf16 v[120:123], v[128:131], v[184:187], 0
	v_mfma_f32_16x16x32_bf16 v[96:99], v[148:151], v[184:187], 0
	v_mfma_f32_16x16x32_bf16 v[116:119], v[128:131], v[192:195], 0
	v_mfma_f32_16x16x32_bf16 v[92:95], v[148:151], v[192:195], 0
	v_mfma_f32_16x16x32_bf16 v[84:87], v[132:135], v[172:175], v[84:87]
	v_mfma_f32_16x16x32_bf16 v[76:79], v[162:165], v[172:175], v[76:79]
	v_mfma_f32_16x16x32_bf16 v[124:127], v[132:135], v[180:183], v[124:127]
	v_mfma_f32_16x16x32_bf16 v[72:75], v[162:165], v[180:183], v[72:75]
	v_mfma_f32_16x16x32_bf16 v[120:123], v[132:135], v[188:191], v[120:123]
	v_mfma_f32_16x16x32_bf16 v[96:99], v[162:165], v[188:191], v[96:99]
	v_mfma_f32_16x16x32_bf16 v[116:119], v[132:135], v[196:199], v[116:119]
	v_mfma_f32_16x16x32_bf16 v[92:95], v[162:165], v[196:199], v[92:95]
	s_setprio 0
	s_barrier
	s_add_i32 s12, s88, s78
	s_mov_b32 m0, s12
	ds_read_b128 v[200:203], v160
	ds_read_b128 v[204:207], v160 offset:1024
	ds_read_b128 v[208:211], v160 offset:2048
	ds_read_b128 v[212:215], v160 offset:3072
	global_load_lds_dwordx4 v138, s[70:71]
	s_add_i32 m0, s12, 0x2000
	s_nop 0
	global_load_lds_dwordx4 v142, s[70:71]
	s_barrier
	s_waitcnt lgkmcnt(0)
	s_setprio 1
	s_waitcnt lgkmcnt(0)
	v_mfma_f32_16x16x32_bf16 v[60:63], v[200:203], v[166:169], 0
	v_mfma_f32_16x16x32_bf16 v[16:19], v[208:211], v[166:169], 0
	v_mfma_f32_16x16x32_bf16 v[56:59], v[200:203], v[176:179], 0
	v_mfma_f32_16x16x32_bf16 v[12:15], v[208:211], v[176:179], 0
	v_mfma_f32_16x16x32_bf16 v[52:55], v[200:203], v[184:187], 0
	v_mfma_f32_16x16x32_bf16 v[28:31], v[208:211], v[184:187], 0
	v_mfma_f32_16x16x32_bf16 v[48:51], v[200:203], v[192:195], 0
	v_mfma_f32_16x16x32_bf16 v[24:27], v[208:211], v[192:195], 0
	v_mfma_f32_16x16x32_bf16 v[60:63], v[204:207], v[172:175], v[60:63]
	v_mfma_f32_16x16x32_bf16 v[16:19], v[212:215], v[172:175], v[16:19]
	v_mfma_f32_16x16x32_bf16 v[56:59], v[204:207], v[180:183], v[56:59]
	v_mfma_f32_16x16x32_bf16 v[12:15], v[212:215], v[180:183], v[12:15]
	v_mfma_f32_16x16x32_bf16 v[52:55], v[204:207], v[188:191], v[52:55]
	v_mfma_f32_16x16x32_bf16 v[28:31], v[212:215], v[188:191], v[28:31]
	v_mfma_f32_16x16x32_bf16 v[48:51], v[204:207], v[196:199], v[48:51]
	v_mfma_f32_16x16x32_bf16 v[24:27], v[212:215], v[196:199], v[24:27]
	s_setprio 0
	s_mov_b32 m0, s67
	s_barrier
	ds_read_b128 v[166:169], v159 offset:16384
	ds_read_b128 v[172:175], v159 offset:17408
	ds_read_b128 v[176:179], v159 offset:18432
	ds_read_b128 v[180:183], v159 offset:19456
	ds_read_b128 v[184:187], v159 offset:20480
	ds_read_b128 v[188:191], v159 offset:21504
	ds_read_b128 v[192:195], v159 offset:22528
	ds_read_b128 v[196:199], v159 offset:23552
	global_load_lds_dwordx4 v136, s[72:73]
	s_mov_b32 m0, s80
	s_nop 0
	global_load_lds_dwordx4 v140, s[72:73]
	s_barrier
	s_waitcnt lgkmcnt(0)
	s_setprio 1
	s_waitcnt lgkmcnt(0)
	v_mfma_f32_16x16x32_bf16 v[112:115], v[128:131], v[166:169], 0
	v_mfma_f32_16x16x32_bf16 v[88:91], v[148:151], v[166:169], 0
	v_mfma_f32_16x16x32_bf16 v[104:107], v[128:131], v[176:179], 0
	v_mfma_f32_16x16x32_bf16 v[80:83], v[148:151], v[176:179], 0
	v_mfma_f32_16x16x32_bf16 v[100:103], v[128:131], v[184:187], 0
	v_mfma_f32_16x16x32_bf16 v[64:67], v[148:151], v[184:187], 0
	v_mfma_f32_16x16x32_bf16 v[108:111], v[128:131], v[192:195], 0
	v_mfma_f32_16x16x32_bf16 v[68:71], v[148:151], v[192:195], 0
	v_mfma_f32_16x16x32_bf16 v[112:115], v[132:135], v[172:175], v[112:115]
	v_mfma_f32_16x16x32_bf16 v[88:91], v[162:165], v[172:175], v[88:91]
	v_mfma_f32_16x16x32_bf16 v[104:107], v[132:135], v[180:183], v[104:107]
	v_mfma_f32_16x16x32_bf16 v[80:83], v[162:165], v[180:183], v[80:83]
	v_mfma_f32_16x16x32_bf16 v[100:103], v[132:135], v[188:191], v[100:103]
	v_mfma_f32_16x16x32_bf16 v[64:67], v[162:165], v[188:191], v[64:67]
	v_mfma_f32_16x16x32_bf16 v[108:111], v[132:135], v[196:199], v[108:111]
	v_mfma_f32_16x16x32_bf16 v[68:71], v[162:165], v[196:199], v[68:71]
	s_setprio 0
	s_barrier
	s_add_u32 s12, s70, 0x40000
	s_addc_u32 s13, s71, 0
	s_add_i32 s52, s89, s78
	s_mov_b32 m0, s52
	s_nop 0
	global_load_lds_dwordx4 v138, s[12:13]
	s_add_i32 m0, s52, 0x2000
	s_nop 0
	global_load_lds_dwordx4 v142, s[12:13]
	s_waitcnt vmcnt(6)
	s_barrier
; #define PG8_STAGE(bufoff, gbase, voff) do { _Pragma("unroll") for (int _i = 0; _i < 2; ++_i) \
;         __builtin_amdgcn_global_load_lds((const unsigned*)((const char*)(gbase) + (voff)[_i]), (LAS unsigned*)(lds + (bufoff) + ldsw + _i * 8192), 16, 0, 0); } while (0)
; #define PG8_LDA(dst, b, h) do { _Pragma("unroll") for (int m = 0; m < 4; ++m) _Pragma("unroll") for (int k = 0; k < 2; ++k) dst[m][k] = *(const LAS bf16x8*)(lds + PG8_SA(b, h) + aoff + m * 2048 + k * 1024); } while (0)
; #define PG8_LDB(dst, b, h) do { _Pragma("unroll") for (int n = 0; n < 2; ++n) _Pragma("unroll") for (int k = 0; k < 2; ++k) dst[n][k] = *(const LAS bf16x8*)(lds + PG8_SB(b, h) + boff + n * 2048 + k * 1024); } while (0)
; #define PG8_MMA(ai, bj, At, Bt) do { __builtin_amdgcn_s_setprio(1); _Pragma("unroll") for (int m = 0; m < 4; ++m) _Pragma("unroll") for (int n = 0; n < 2; ++n) _Pragma("unroll") for (int k = 0; k < 2; ++k) \
;         acc[ai][bj][m][n] = __builtin_amdgcn_mfma_f32_16x16x32_bf16(Bt[n][k], At[m][k], acc[ai][bj][m][n], 0, 0, 0); __builtin_amdgcn_s_setprio(0); } while (0)
; #define PG8_WAIT_V(n) asm volatile("s_waitcnt vmcnt(" #n ")" ::: "memory")
; #define PG8_WAIT_L(n) asm volatile("s_waitcnt lgkmcnt(" #n ")" ::: "memory")
; #define PG8_BAR __builtin_amdgcn_s_barrier()
; #define PG8_SCHED __builtin_amdgcn_sched_barrier(0)
; template <class Epi, class Sched>
; __device__ __forceinline__ void gemm_phase(LAS unsigned char* lds, const int K, const Sched& S, const Epi& E) {
;     ...
;             PG8_WAIT_V(6); PG8_BAR; PG8_MMA(1, 1, At, B1); PG8_BAR;
;             PG8_LDB(B0, 1, 0); PG8_SCHED; PG8_LDA(At, 1, 0); PG8_STAGE(PG8_SA(0, 1), a2 + hstepA, voffA);
;             PG8_WAIT_L(8); PG8_BAR; PG8_WAIT_L(0); PG8_MMA(0, 0, At, B0); PG8_BAR; PG8_SCHED;
;             PG8_LDB(B1, 1, 1); PG8_STAGE(PG8_SB(1, 0), b3, voffB);
;             PG8_BAR; PG8_WAIT_L(0); PG8_MMA(0, 1, At, B1); PG8_BAR;
;             PG8_LDA(At, 1, 1); PG8_STAGE(PG8_SA(1, 0), a3, voffA);
;             PG8_BAR; PG8_WAIT_L(0); PG8_MMA(1, 0, At, B0); PG8_BAR; PG8_SCHED;
	s_setprio 1
	v_mfma_f32_16x16x32_bf16 v[44:47], v[200:203], v[166:169], 0
	v_mfma_f32_16x16x32_bf16 v[20:23], v[208:211], v[166:169], 0
	v_mfma_f32_16x16x32_bf16 v[40:43], v[200:203], v[176:179], 0
	v_mfma_f32_16x16x32_bf16 v[8:11], v[208:211], v[176:179], 0
	v_mfma_f32_16x16x32_bf16 v[36:39], v[200:203], v[184:187], 0
	v_mfma_f32_16x16x32_bf16 v[0:3], v[208:211], v[184:187], 0
	v_mfma_f32_16x16x32_bf16 v[32:35], v[200:203], v[192:195], 0
	v_mfma_f32_16x16x32_bf16 v[4:7], v[208:211], v[192:195], 0
	v_mfma_f32_16x16x32_bf16 v[44:47], v[204:207], v[172:175], v[44:47]
	v_mfma_f32_16x16x32_bf16 v[20:23], v[212:215], v[172:175], v[20:23]
	v_mfma_f32_16x16x32_bf16 v[40:43], v[204:207], v[180:183], v[40:43]
	v_mfma_f32_16x16x32_bf16 v[8:11], v[212:215], v[180:183], v[8:11]
	v_mfma_f32_16x16x32_bf16 v[36:39], v[204:207], v[188:191], v[36:39]
	v_mfma_f32_16x16x32_bf16 v[0:3], v[212:215], v[188:191], v[0:3]
	v_mfma_f32_16x16x32_bf16 v[32:35], v[204:207], v[196:199], v[32:35]
	v_mfma_f32_16x16x32_bf16 v[4:7], v[212:215], v[196:199], v[4:7]
	s_setprio 0
	s_add_i32 s52, 0, 0x18000
	v_add_u32_e32 v161, s52, v156
	s_barrier
	ds_read_b128 v[128:131], v161
	ds_read_b128 v[132:135], v161 offset:1024
	ds_read_b128 v[148:151], v161 offset:2048
	ds_read_b128 v[162:165], v161 offset:3072
	s_add_u32 s12, s72, 0x20000
	s_addc_u32 s13, s73, 0
	s_mov_b32 m0, s81
	ds_read_b128 v[166:169], v159 offset:32768
	ds_read_b128 v[172:175], v159 offset:33792
	ds_read_b128 v[176:179], v159 offset:34816
	ds_read_b128 v[180:183], v159 offset:35840
	ds_read_b128 v[184:187], v159 offset:36864
	ds_read_b128 v[188:191], v159 offset:37888
	ds_read_b128 v[192:195], v159 offset:38912
	ds_read_b128 v[196:199], v159 offset:39936
	global_load_lds_dwordx4 v136, s[12:13]
	s_mov_b32 m0, s82
	s_nop 0
	global_load_lds_dwordx4 v140, s[12:13]
	s_waitcnt lgkmcnt(8)
	s_barrier
	s_waitcnt lgkmcnt(0)
	s_setprio 1
	s_waitcnt lgkmcnt(0)
	v_mfma_f32_16x16x32_bf16 v[84:87], v[128:131], v[166:169], v[84:87]
	v_mfma_f32_16x16x32_bf16 v[76:79], v[148:151], v[166:169], v[76:79]
	v_mfma_f32_16x16x32_bf16 v[124:127], v[128:131], v[176:179], v[124:127]
	v_mfma_f32_16x16x32_bf16 v[72:75], v[148:151], v[176:179], v[72:75]
	v_mfma_f32_16x16x32_bf16 v[120:123], v[128:131], v[184:187], v[120:123]
	v_mfma_f32_16x16x32_bf16 v[96:99], v[148:151], v[184:187], v[96:99]
	v_mfma_f32_16x16x32_bf16 v[116:119], v[128:131], v[192:195], v[116:119]
	v_mfma_f32_16x16x32_bf16 v[92:95], v[148:151], v[192:195], v[92:95]
	v_mfma_f32_16x16x32_bf16 v[84:87], v[132:135], v[172:175], v[84:87]
	v_mfma_f32_16x16x32_bf16 v[76:79], v[162:165], v[172:175], v[76:79]
	v_mfma_f32_16x16x32_bf16 v[124:127], v[132:135], v[180:183], v[124:127]
	v_mfma_f32_16x16x32_bf16 v[72:75], v[162:165], v[180:183], v[72:75]
	v_mfma_f32_16x16x32_bf16 v[120:123], v[132:135], v[188:191], v[120:123]
	v_mfma_f32_16x16x32_bf16 v[96:99], v[162:165], v[188:191], v[96:99]
	v_mfma_f32_16x16x32_bf16 v[116:119], v[132:135], v[196:199], v[116:119]
	v_mfma_f32_16x16x32_bf16 v[92:95], v[162:165], v[196:199], v[92:95]
	s_setprio 0
	s_barrier
	s_add_i32 s53, 0, 0x1c000
	s_add_i32 s12, s52, s78
	v_add_u32_e32 v161, s53, v156
	s_mov_b32 m0, s12
	ds_read_b128 v[200:203], v161
	ds_read_b128 v[204:207], v161 offset:1024
	ds_read_b128 v[208:211], v161 offset:2048
	ds_read_b128 v[212:215], v161 offset:3072
	s_add_u32 s98, s70, 0x80
	s_addc_u32 s99, s71, 0
	global_load_lds_dwordx4 v138, s[98:99]
	s_add_i32 m0, s12, 0x2000
	s_nop 0
	global_load_lds_dwordx4 v142, s[98:99]
	s_barrier
	s_waitcnt lgkmcnt(0)
	s_setprio 1
	s_waitcnt lgkmcnt(0)
	v_mfma_f32_16x16x32_bf16 v[60:63], v[200:203], v[166:169], v[60:63]
	v_mfma_f32_16x16x32_bf16 v[16:19], v[208:211], v[166:169], v[16:19]
	v_mfma_f32_16x16x32_bf16 v[56:59], v[200:203], v[176:179], v[56:59]
	v_mfma_f32_16x16x32_bf16 v[12:15], v[208:211], v[176:179], v[12:15]
	v_mfma_f32_16x16x32_bf16 v[52:55], v[200:203], v[184:187], v[52:55]
	v_mfma_f32_16x16x32_bf16 v[28:31], v[208:211], v[184:187], v[28:31]
	v_mfma_f32_16x16x32_bf16 v[48:51], v[200:203], v[192:195], v[48:51]
	v_mfma_f32_16x16x32_bf16 v[24:27], v[208:211], v[192:195], v[24:27]
	v_mfma_f32_16x16x32_bf16 v[60:63], v[204:207], v[172:175], v[60:63]
	v_mfma_f32_16x16x32_bf16 v[16:19], v[212:215], v[172:175], v[16:19]
	v_mfma_f32_16x16x32_bf16 v[56:59], v[204:207], v[180:183], v[56:59]
	v_mfma_f32_16x16x32_bf16 v[12:15], v[212:215], v[180:183], v[12:15]
	v_mfma_f32_16x16x32_bf16 v[52:55], v[204:207], v[188:191], v[52:55]
	v_mfma_f32_16x16x32_bf16 v[28:31], v[212:215], v[188:191], v[28:31]
	v_mfma_f32_16x16x32_bf16 v[48:51], v[204:207], v[196:199], v[48:51]
	v_mfma_f32_16x16x32_bf16 v[24:27], v[212:215], v[196:199], v[24:27]
	s_setprio 0
	s_mov_b32 m0, s84
	s_barrier
	ds_read_b128 v[166:169], v159 offset:49152
	ds_read_b128 v[172:175], v159 offset:50176
	ds_read_b128 v[176:179], v159 offset:51200
	ds_read_b128 v[180:183], v159 offset:52224
	ds_read_b128 v[184:187], v159 offset:53248
	ds_read_b128 v[188:191], v159 offset:54272
	ds_read_b128 v[192:195], v159 offset:55296
	ds_read_b128 v[196:199], v159 offset:56320
	s_add_u32 s98, s72, 0x80
	s_addc_u32 s99, s73, 0
	global_load_lds_dwordx4 v136, s[98:99]
	s_mov_b32 m0, s85
	s_nop 0
	global_load_lds_dwordx4 v140, s[98:99]
	s_barrier
; #define PG8_STAGE(bufoff, gbase, voff) do { _Pragma("unroll") for (int _i = 0; _i < 2; ++_i) \
;         __builtin_amdgcn_global_load_lds((const unsigned*)((const char*)(gbase) + (voff)[_i]), (LAS unsigned*)(lds + (bufoff) + ldsw + _i * 8192), 16, 0, 0); } while (0)
; #define PG8_LDA(dst, b, h) do { _Pragma("unroll") for (int m = 0; m < 4; ++m) _Pragma("unroll") for (int k = 0; k < 2; ++k) dst[m][k] = *(const LAS bf16x8*)(lds + PG8_SA(b, h) + aoff + m * 2048 + k * 1024); } while (0)
; #define PG8_LDB(dst, b, h) do { _Pragma("unroll") for (int n = 0; n < 2; ++n) _Pragma("unroll") for (int k = 0; k < 2; ++k) dst[n][k] = *(const LAS bf16x8*)(lds + PG8_SB(b, h) + boff + n * 2048 + k * 1024); } while (0)
; #define PG8_MMA(ai, bj, At, Bt) do { __builtin_amdgcn_s_setprio(1); _Pragma("unroll") for (int m = 0; m < 4; ++m) _Pragma("unroll") for (int n = 0; n < 2; ++n) _Pragma("unroll") for (int k = 0; k < 2; ++k) \
;         acc[ai][bj][m][n] = __builtin_amdgcn_mfma_f32_16x16x32_bf16(Bt[n][k], At[m][k], acc[ai][bj][m][n], 0, 0, 0); __builtin_amdgcn_s_setprio(0); } while (0)
; #define PG8_WAIT_V(n) asm volatile("s_waitcnt vmcnt(" #n ")" ::: "memory")
; #define PG8_WAIT_L(n) asm volatile("s_waitcnt lgkmcnt(" #n ")" ::: "memory")
; #define PG8_BAR __builtin_amdgcn_s_barrier()
; #define PG8_SCHED __builtin_amdgcn_sched_barrier(0)
; template <class Epi, class Sched>
; __device__ __forceinline__ void gemm_phase(LAS unsigned char* lds, const int K, const Sched& S, const Epi& E) {
;     ...
;             PG8_LDB(B0, 0, 0); PG8_SCHED; PG8_LDA(At, 0, 0); PG8_STAGE(PG8_SA(1, 1), a1 + hstepA, voffA);
;             PG8_WAIT_L(8); PG8_BAR; PG8_WAIT_L(0); PG8_MMA(0, 0, At, B0); PG8_BAR; PG8_SCHED;
;             PG8_LDB(B1, 0, 1); PG8_STAGE(PG8_SB(0, 0), b2, voffB);
;     ...
;             PG8_BAR; PG8_WAIT_L(0); PG8_MMA(1, 0, At, B0); PG8_BAR; PG8_SCHED;
;             PG8_STAGE(PG8_SB(1, 1), b3 + hstep, voffB);
;             PG8_WAIT_V(6); PG8_BAR; PG8_MMA(1, 1, At, B1); PG8_BAR;
	s_waitcnt lgkmcnt(0)
	s_setprio 1
	s_waitcnt lgkmcnt(0)
	v_mfma_f32_16x16x32_bf16 v[112:115], v[128:131], v[166:169], v[112:115]
	v_mfma_f32_16x16x32_bf16 v[88:91], v[148:151], v[166:169], v[88:91]
	v_mfma_f32_16x16x32_bf16 v[104:107], v[128:131], v[176:179], v[104:107]
	v_mfma_f32_16x16x32_bf16 v[80:83], v[148:151], v[176:179], v[80:83]
	v_mfma_f32_16x16x32_bf16 v[100:103], v[128:131], v[184:187], v[100:103]
	v_mfma_f32_16x16x32_bf16 v[64:67], v[148:151], v[184:187], v[64:67]
	v_mfma_f32_16x16x32_bf16 v[108:111], v[128:131], v[192:195], v[108:111]
	v_mfma_f32_16x16x32_bf16 v[68:71], v[148:151], v[192:195], v[68:71]
	v_mfma_f32_16x16x32_bf16 v[112:115], v[132:135], v[172:175], v[112:115]
	v_mfma_f32_16x16x32_bf16 v[88:91], v[162:165], v[172:175], v[88:91]
	v_mfma_f32_16x16x32_bf16 v[104:107], v[132:135], v[180:183], v[104:107]
	v_mfma_f32_16x16x32_bf16 v[80:83], v[162:165], v[180:183], v[80:83]
	v_mfma_f32_16x16x32_bf16 v[100:103], v[132:135], v[188:191], v[100:103]
	v_mfma_f32_16x16x32_bf16 v[64:67], v[162:165], v[188:191], v[64:67]
	v_mfma_f32_16x16x32_bf16 v[108:111], v[132:135], v[196:199], v[108:111]
	v_mfma_f32_16x16x32_bf16 v[68:71], v[162:165], v[196:199], v[68:71]
	s_setprio 0
	s_barrier
	s_add_u32 s12, s70, 0x40080
	s_addc_u32 s13, s71, 0
	s_add_i32 s52, s53, s78
	s_mov_b32 m0, s52
	s_nop 0
	global_load_lds_dwordx4 v138, s[12:13]
	s_add_i32 m0, s52, 0x2000
	s_nop 0
	global_load_lds_dwordx4 v142, s[12:13]
	s_waitcnt vmcnt(6)
	s_barrier
	s_setprio 1
	v_mfma_f32_16x16x32_bf16 v[44:47], v[200:203], v[166:169], v[44:47]
	v_mfma_f32_16x16x32_bf16 v[20:23], v[208:211], v[166:169], v[20:23]
	v_mfma_f32_16x16x32_bf16 v[40:43], v[200:203], v[176:179], v[40:43]
	v_mfma_f32_16x16x32_bf16 v[8:11], v[208:211], v[176:179], v[8:11]
	v_mfma_f32_16x16x32_bf16 v[36:39], v[200:203], v[184:187], v[36:39]
	v_mfma_f32_16x16x32_bf16 v[0:3], v[208:211], v[184:187], v[0:3]
	v_mfma_f32_16x16x32_bf16 v[32:35], v[200:203], v[192:195], v[32:35]
	v_mfma_f32_16x16x32_bf16 v[4:7], v[208:211], v[192:195], v[4:7]
	v_mfma_f32_16x16x32_bf16 v[44:47], v[204:207], v[172:175], v[44:47]
	v_mfma_f32_16x16x32_bf16 v[20:23], v[212:215], v[172:175], v[20:23]
	v_mfma_f32_16x16x32_bf16 v[40:43], v[204:207], v[180:183], v[40:43]
	v_mfma_f32_16x16x32_bf16 v[8:11], v[212:215], v[180:183], v[8:11]
	v_mfma_f32_16x16x32_bf16 v[36:39], v[204:207], v[188:191], v[36:39]
	v_mfma_f32_16x16x32_bf16 v[0:3], v[212:215], v[188:191], v[0:3]
	v_mfma_f32_16x16x32_bf16 v[32:35], v[204:207], v[196:199], v[32:35]
	v_mfma_f32_16x16x32_bf16 v[4:7], v[212:215], v[196:199], v[4:7]
	s_setprio 0
	s_add_i32 s49, s49, 2
	s_add_u32 s11, s11, 0x100
	s_addc_u32 s33, s33, 0
	s_cmp_gt_u32 s49, 13
	s_mov_b64 s[12:13], s[68:69]
	s_barrier
.LBB0_800:
	ds_read_b128 v[128:131], v158
	ds_read_b128 v[132:135], v158 offset:1024
	ds_read_b128 v[148:151], v158 offset:2048
	ds_read_b128 v[162:165], v158 offset:3072
	s_add_u32 s68, s12, 0x100
	s_addc_u32 s69, s13, 0
	s_cmp_eq_u32 s49, 12
	s_cselect_b32 s73, s63, s69
	s_cselect_b32 s72, s62, s68
	s_cselect_b32 s71, s65, s33
	s_cselect_b32 s70, s64, s11
	s_add_i32 m0, s67, 0xc000
	ds_read_b128 v[166:169], v159
	ds_read_b128 v[172:175], v159 offset:1024
	ds_read_b128 v[176:179], v159 offset:2048
	ds_read_b128 v[180:183], v159 offset:3072
	ds_read_b128 v[184:187], v159 offset:4096
	ds_read_b128 v[188:191], v159 offset:5120
	ds_read_b128 v[192:195], v159 offset:6144
	ds_read_b128 v[196:199], v159 offset:7168
	global_load_lds_dwordx4 v144, s[12:13]
	s_add_i32 m0, s67, 0xe000
	s_nop 0
	global_load_lds_dwordx4 v146, s[12:13]
	s_waitcnt lgkmcnt(8)
	s_barrier
	s_waitcnt lgkmcnt(0)
	s_setprio 1
	s_waitcnt lgkmcnt(0)
	v_mfma_f32_16x16x32_bf16 v[84:87], v[128:131], v[166:169], v[84:87]
	v_mfma_f32_16x16x32_bf16 v[76:79], v[148:151], v[166:169], v[76:79]
	v_mfma_f32_16x16x32_bf16 v[124:127], v[128:131], v[176:179], v[124:127]
	v_mfma_f32_16x16x32_bf16 v[72:75], v[148:151], v[176:179], v[72:75]
	v_mfma_f32_16x16x32_bf16 v[120:123], v[128:131], v[184:187], v[120:123]
	v_mfma_f32_16x16x32_bf16 v[96:99], v[148:151], v[184:187], v[96:99]
	v_mfma_f32_16x16x32_bf16 v[116:119], v[128:131], v[192:195], v[116:119]
	v_mfma_f32_16x16x32_bf16 v[92:95], v[148:151], v[192:195], v[92:95]
	v_mfma_f32_16x16x32_bf16 v[84:87], v[132:135], v[172:175], v[84:87]
	v_mfma_f32_16x16x32_bf16 v[76:79], v[162:165], v[172:175], v[76:79]
	v_mfma_f32_16x16x32_bf16 v[124:127], v[132:135], v[180:183], v[124:127]
	v_mfma_f32_16x16x32_bf16 v[72:75], v[162:165], v[180:183], v[72:75]
	v_mfma_f32_16x16x32_bf16 v[120:123], v[132:135], v[188:191], v[120:123]
	v_mfma_f32_16x16x32_bf16 v[96:99], v[162:165], v[188:191], v[96:99]
	v_mfma_f32_16x16x32_bf16 v[116:119], v[132:135], v[196:199], v[116:119]
	v_mfma_f32_16x16x32_bf16 v[92:95], v[162:165], v[196:199], v[92:95]
	s_setprio 0
	s_barrier
	s_add_i32 s12, s88, s78
	s_mov_b32 m0, s12
	ds_read_b128 v[200:203], v160
	ds_read_b128 v[204:207], v160 offset:1024
	ds_read_b128 v[208:211], v160 offset:2048
	ds_read_b128 v[212:215], v160 offset:3072
	global_load_lds_dwordx4 v138, s[70:71]
	s_add_i32 m0, s12, 0x2000
	s_nop 0
	global_load_lds_dwordx4 v142, s[70:71]
	s_barrier
; #define PG8_STAGE(bufoff, gbase, voff) do { _Pragma("unroll") for (int _i = 0; _i < 2; ++_i) \
;         __builtin_amdgcn_global_load_lds((const unsigned*)((const char*)(gbase) + (voff)[_i]), (LAS unsigned*)(lds + (bufoff) + ldsw + _i * 8192), 16, 0, 0); } while (0)
; #define PG8_LDA(dst, b, h) do { _Pragma("unroll") for (int m = 0; m < 4; ++m) _Pragma("unroll") for (int k = 0; k < 2; ++k) dst[m][k] = *(const LAS bf16x8*)(lds + PG8_SA(b, h) + aoff + m * 2048 + k * 1024); } while (0)
; #define PG8_LDB(dst, b, h) do { _Pragma("unroll") for (int n = 0; n < 2; ++n) _Pragma("unroll") for (int k = 0; k < 2; ++k) dst[n][k] = *(const LAS bf16x8*)(lds + PG8_SB(b, h) + boff + n * 2048 + k * 1024); } while (0)
; #define PG8_MMA(ai, bj, At, Bt) do { __builtin_amdgcn_s_setprio(1); _Pragma("unroll") for (int m = 0; m < 4; ++m) _Pragma("unroll") for (int n = 0; n < 2; ++n) _Pragma("unroll") for (int k = 0; k < 2; ++k) \
;         acc[ai][bj][m][n] = __builtin_amdgcn_mfma_f32_16x16x32_bf16(Bt[n][k], At[m][k], acc[ai][bj][m][n], 0, 0, 0); __builtin_amdgcn_s_setprio(0); } while (0)
; #define PG8_WAIT_V(n) asm volatile("s_waitcnt vmcnt(" #n ")" ::: "memory")
; #define PG8_WAIT_L(n) asm volatile("s_waitcnt lgkmcnt(" #n ")" ::: "memory")
; #define PG8_BAR __builtin_amdgcn_s_barrier()
; #define PG8_SCHED __builtin_amdgcn_sched_barrier(0)
; template <class Epi, class Sched>
; __device__ __forceinline__ void gemm_phase(LAS unsigned char* lds, const int K, const Sched& S, const Epi& E) {
;     ...
;             PG8_BAR; PG8_WAIT_L(0); PG8_MMA(0, 1, At, B1); PG8_BAR;
;             PG8_LDA(At, 0, 1); PG8_STAGE(PG8_SA(0, 0), a2, voffA);
;             PG8_BAR; PG8_WAIT_L(0); PG8_MMA(1, 0, At, B0); PG8_BAR; PG8_SCHED;
;             PG8_STAGE(PG8_SB(0, 1), b2 + hstep, voffB);
;             PG8_WAIT_V(6); PG8_BAR; PG8_MMA(1, 1, At, B1); PG8_BAR;
;             PG8_LDB(B0, 1, 0); PG8_SCHED; PG8_LDA(At, 1, 0); PG8_STAGE(PG8_SA(0, 1), a2 + hstepA, voffA);
;             PG8_WAIT_L(8); PG8_BAR; PG8_WAIT_L(0); PG8_MMA(0, 0, At, B0); PG8_BAR; PG8_SCHED;
;             PG8_LDB(B1, 1, 1); PG8_STAGE(PG8_SB(1, 0), b3, voffB);
	s_waitcnt lgkmcnt(0)
	s_setprio 1
	s_waitcnt lgkmcnt(0)
	v_mfma_f32_16x16x32_bf16 v[60:63], v[200:203], v[166:169], v[60:63]
	v_mfma_f32_16x16x32_bf16 v[16:19], v[208:211], v[166:169], v[16:19]
	v_mfma_f32_16x16x32_bf16 v[56:59], v[200:203], v[176:179], v[56:59]
	v_mfma_f32_16x16x32_bf16 v[12:15], v[208:211], v[176:179], v[12:15]
	v_mfma_f32_16x16x32_bf16 v[52:55], v[200:203], v[184:187], v[52:55]
	v_mfma_f32_16x16x32_bf16 v[28:31], v[208:211], v[184:187], v[28:31]
	v_mfma_f32_16x16x32_bf16 v[48:51], v[200:203], v[192:195], v[48:51]
	v_mfma_f32_16x16x32_bf16 v[24:27], v[208:211], v[192:195], v[24:27]
	v_mfma_f32_16x16x32_bf16 v[60:63], v[204:207], v[172:175], v[60:63]
	v_mfma_f32_16x16x32_bf16 v[16:19], v[212:215], v[172:175], v[16:19]
	v_mfma_f32_16x16x32_bf16 v[56:59], v[204:207], v[180:183], v[56:59]
	v_mfma_f32_16x16x32_bf16 v[12:15], v[212:215], v[180:183], v[12:15]
	v_mfma_f32_16x16x32_bf16 v[52:55], v[204:207], v[188:191], v[52:55]
	v_mfma_f32_16x16x32_bf16 v[28:31], v[212:215], v[188:191], v[28:31]
	v_mfma_f32_16x16x32_bf16 v[48:51], v[204:207], v[196:199], v[48:51]
	v_mfma_f32_16x16x32_bf16 v[24:27], v[212:215], v[196:199], v[24:27]
	s_setprio 0
	s_mov_b32 m0, s67
	s_barrier
	ds_read_b128 v[166:169], v159 offset:16384
	ds_read_b128 v[172:175], v159 offset:17408
	ds_read_b128 v[176:179], v159 offset:18432
	ds_read_b128 v[180:183], v159 offset:19456
	ds_read_b128 v[184:187], v159 offset:20480
	ds_read_b128 v[188:191], v159 offset:21504
	ds_read_b128 v[192:195], v159 offset:22528
	ds_read_b128 v[196:199], v159 offset:23552
	global_load_lds_dwordx4 v136, s[72:73]
	s_mov_b32 m0, s80
	s_nop 0
	global_load_lds_dwordx4 v140, s[72:73]
	s_barrier
	s_waitcnt lgkmcnt(0)
	s_setprio 1
	s_waitcnt lgkmcnt(0)
	v_mfma_f32_16x16x32_bf16 v[112:115], v[128:131], v[166:169], v[112:115]
	v_mfma_f32_16x16x32_bf16 v[88:91], v[148:151], v[166:169], v[88:91]
	v_mfma_f32_16x16x32_bf16 v[104:107], v[128:131], v[176:179], v[104:107]
	v_mfma_f32_16x16x32_bf16 v[80:83], v[148:151], v[176:179], v[80:83]
	v_mfma_f32_16x16x32_bf16 v[100:103], v[128:131], v[184:187], v[100:103]
	v_mfma_f32_16x16x32_bf16 v[64:67], v[148:151], v[184:187], v[64:67]
	v_mfma_f32_16x16x32_bf16 v[108:111], v[128:131], v[192:195], v[108:111]
	v_mfma_f32_16x16x32_bf16 v[68:71], v[148:151], v[192:195], v[68:71]
	v_mfma_f32_16x16x32_bf16 v[112:115], v[132:135], v[172:175], v[112:115]
	v_mfma_f32_16x16x32_bf16 v[88:91], v[162:165], v[172:175], v[88:91]
	v_mfma_f32_16x16x32_bf16 v[104:107], v[132:135], v[180:183], v[104:107]
	v_mfma_f32_16x16x32_bf16 v[80:83], v[162:165], v[180:183], v[80:83]
	v_mfma_f32_16x16x32_bf16 v[100:103], v[132:135], v[188:191], v[100:103]
	v_mfma_f32_16x16x32_bf16 v[64:67], v[162:165], v[188:191], v[64:67]
	v_mfma_f32_16x16x32_bf16 v[108:111], v[132:135], v[196:199], v[108:111]
	v_mfma_f32_16x16x32_bf16 v[68:71], v[162:165], v[196:199], v[68:71]
	s_setprio 0
	s_barrier
	s_add_u32 s12, s70, 0x40000
	s_addc_u32 s13, s71, 0
	s_add_i32 s52, s89, s78
	s_mov_b32 m0, s52
	s_nop 0
	global_load_lds_dwordx4 v138, s[12:13]
	s_add_i32 m0, s52, 0x2000
	s_nop 0
	global_load_lds_dwordx4 v142, s[12:13]
	s_waitcnt vmcnt(6)
	s_barrier
	s_setprio 1
	v_mfma_f32_16x16x32_bf16 v[44:47], v[200:203], v[166:169], v[44:47]
	v_mfma_f32_16x16x32_bf16 v[20:23], v[208:211], v[166:169], v[20:23]
	v_mfma_f32_16x16x32_bf16 v[40:43], v[200:203], v[176:179], v[40:43]
	v_mfma_f32_16x16x32_bf16 v[8:11], v[208:211], v[176:179], v[8:11]
	v_mfma_f32_16x16x32_bf16 v[36:39], v[200:203], v[184:187], v[36:39]
	v_mfma_f32_16x16x32_bf16 v[0:3], v[208:211], v[184:187], v[0:3]
	v_mfma_f32_16x16x32_bf16 v[32:35], v[200:203], v[192:195], v[32:35]
	v_mfma_f32_16x16x32_bf16 v[4:7], v[208:211], v[192:195], v[4:7]
	v_mfma_f32_16x16x32_bf16 v[44:47], v[204:207], v[172:175], v[44:47]
	v_mfma_f32_16x16x32_bf16 v[20:23], v[212:215], v[172:175], v[20:23]
	v_mfma_f32_16x16x32_bf16 v[40:43], v[204:207], v[180:183], v[40:43]
	v_mfma_f32_16x16x32_bf16 v[8:11], v[212:215], v[180:183], v[8:11]
	v_mfma_f32_16x16x32_bf16 v[36:39], v[204:207], v[188:191], v[36:39]
	v_mfma_f32_16x16x32_bf16 v[0:3], v[212:215], v[188:191], v[0:3]
	v_mfma_f32_16x16x32_bf16 v[32:35], v[204:207], v[196:199], v[32:35]
	v_mfma_f32_16x16x32_bf16 v[4:7], v[212:215], v[196:199], v[4:7]
	s_setprio 0
	s_add_i32 s52, 0, 0x18000
	v_add_u32_e32 v161, s52, v156
	s_barrier
	ds_read_b128 v[128:131], v161
	ds_read_b128 v[132:135], v161 offset:1024
	ds_read_b128 v[148:151], v161 offset:2048
	ds_read_b128 v[162:165], v161 offset:3072
	s_add_u32 s12, s72, 0x20000
	s_addc_u32 s13, s73, 0
	s_mov_b32 m0, s81
	ds_read_b128 v[166:169], v159 offset:32768
	ds_read_b128 v[172:175], v159 offset:33792
	ds_read_b128 v[176:179], v159 offset:34816
	ds_read_b128 v[180:183], v159 offset:35840
	ds_read_b128 v[184:187], v159 offset:36864
	ds_read_b128 v[188:191], v159 offset:37888
	ds_read_b128 v[192:195], v159 offset:38912
	ds_read_b128 v[196:199], v159 offset:39936
	global_load_lds_dwordx4 v136, s[12:13]
	s_mov_b32 m0, s82
	s_nop 0
	global_load_lds_dwordx4 v140, s[12:13]
	s_waitcnt lgkmcnt(8)
	s_barrier
; __device__ __forceinline__ unsigned cvt_pk_bf16(float lo, float hi) { unsigned r; asm volatile("v_cvt_pk_bf16_f32 %0, %1, %2" : "=v"(r) : "v"(lo), "v"(hi)); return r; }
; #define PG8_STAGE(bufoff, gbase, voff) do { _Pragma("unroll") for (int _i = 0; _i < 2; ++_i) \
;         __builtin_amdgcn_global_load_lds((const unsigned*)((const char*)(gbase) + (voff)[_i]), (LAS unsigned*)(lds + (bufoff) + ldsw + _i * 8192), 16, 0, 0); } while (0)
; template <class Epi, class Sched>
; __device__ __forceinline__ void gemm_phase(LAS unsigned char* lds, const int K, const Sched& S, const Epi& E) {
;     ...
;             PG8_WAIT_L(8); PG8_BAR; PG8_WAIT_L(0); PG8_MMA(0, 0, At, B0); PG8_BAR; PG8_SCHED;
;             PG8_LDB(B1, 1, 1); PG8_STAGE(PG8_SB(1, 0), b3, voffB);
;             PG8_BAR; PG8_WAIT_L(0); PG8_MMA(0, 1, At, B1); PG8_BAR;
;             PG8_LDA(At, 1, 1); PG8_STAGE(PG8_SA(1, 0), a3, voffA);
;             PG8_BAR; PG8_WAIT_L(0); PG8_MMA(1, 0, At, B0); PG8_BAR; PG8_SCHED;
;             PG8_STAGE(PG8_SB(1, 1), b3 + hstep, voffB);
;             PG8_WAIT_V(6); PG8_BAR; PG8_MMA(1, 1, At, B1); PG8_BAR;
;     __device__ __forceinline__ void operator()(f32x4 (&acc)[2][2][4][2], const Unit& u, int wr, int wc, int fr, int fq) const {
;         const int J0 = u.pn * 128 + wc * 32 + fq * 8, sc = u.pm * 2 + wr;
;         const bool f0 = (fr == 0), f15 = (fr == 15);
;         if (f0 || f15) {
; #pragma unroll
;             for (int bj = 0; bj < 2; ++bj)
; #pragma unroll
;                 for (int q = 0; q < 2; ++q) { const f32x4 a0 = f0 ? acc[0][bj][q][0] : acc[1][bj][2 + q][0], a1 = f0 ? acc[0][bj][q][1] : acc[1][bj][2 + q][1];
;                     u32x4 w; w.x = cvt_pk_bf16(a0[0], a0[1]); w.y = cvt_pk_bf16(a0[2], a0[3]); w.z = cvt_pk_bf16(a1[0], a1[1]); w.w = cvt_pk_bf16(a1[2], a1[3]);
;                     *(u32x4*)(side + (size_t)(sc * 4 + (f0 ? q : 2 + q)) * (2 * DFF) + bj * DFF + J0) = w; }
;         }
; #pragma unroll
;         for (int bj = 0; bj < 2; ++bj)
; #pragma unroll
;             for (int n = 0; n < 2; ++n) {
;                 const int col = bj * DFF + J0 + n * 4;
;                 const float csc = bj ? 0.6931471805599453f : 1.4426950408889634f;
;                 const f32x4 k0 = *(const f32x4*)(cw + col) * csc, k1 = *(const f32x4*)(cw + 2 * DFF + col) * csc, k2 = *(const f32x4*)(cw + 4 * DFF + col) * csc, kb = *(const f32x4*)(cb + col) * csc;
	s_waitcnt lgkmcnt(0)
	s_setprio 1
	s_waitcnt lgkmcnt(0)
	v_mfma_f32_16x16x32_bf16 v[84:87], v[128:131], v[166:169], v[84:87]
	v_mfma_f32_16x16x32_bf16 v[76:79], v[148:151], v[166:169], v[76:79]
	v_mfma_f32_16x16x32_bf16 v[124:127], v[128:131], v[176:179], v[124:127]
	v_mfma_f32_16x16x32_bf16 v[72:75], v[148:151], v[176:179], v[72:75]
	v_mfma_f32_16x16x32_bf16 v[120:123], v[128:131], v[184:187], v[120:123]
	v_mfma_f32_16x16x32_bf16 v[96:99], v[148:151], v[184:187], v[96:99]
	v_mfma_f32_16x16x32_bf16 v[116:119], v[128:131], v[192:195], v[116:119]
	v_mfma_f32_16x16x32_bf16 v[92:95], v[148:151], v[192:195], v[92:95]
	v_mfma_f32_16x16x32_bf16 v[84:87], v[132:135], v[172:175], v[84:87]
	v_mfma_f32_16x16x32_bf16 v[76:79], v[162:165], v[172:175], v[76:79]
	v_mfma_f32_16x16x32_bf16 v[124:127], v[132:135], v[180:183], v[124:127]
	v_mfma_f32_16x16x32_bf16 v[72:75], v[162:165], v[180:183], v[72:75]
	v_mfma_f32_16x16x32_bf16 v[120:123], v[132:135], v[188:191], v[120:123]
	v_mfma_f32_16x16x32_bf16 v[96:99], v[162:165], v[188:191], v[96:99]
	v_mfma_f32_16x16x32_bf16 v[116:119], v[132:135], v[196:199], v[116:119]
	v_mfma_f32_16x16x32_bf16 v[92:95], v[162:165], v[196:199], v[92:95]
	s_setprio 0
	s_barrier
	s_add_i32 s53, 0, 0x1c000
	s_add_i32 s12, s52, s78
	v_add_u32_e32 v161, s53, v156
	s_mov_b32 m0, s12
	ds_read_b128 v[200:203], v161
	ds_read_b128 v[204:207], v161 offset:1024
	ds_read_b128 v[208:211], v161 offset:2048
	ds_read_b128 v[212:215], v161 offset:3072
	s_add_u32 s98, s70, 0x80
	s_addc_u32 s99, s71, 0
	global_load_lds_dwordx4 v138, s[98:99]
	s_add_i32 m0, s12, 0x2000
	s_nop 0
	global_load_lds_dwordx4 v142, s[98:99]
	s_barrier
	s_waitcnt lgkmcnt(0)
	s_setprio 1
	s_waitcnt lgkmcnt(0)
	v_mfma_f32_16x16x32_bf16 v[60:63], v[200:203], v[166:169], v[60:63]
	v_mfma_f32_16x16x32_bf16 v[16:19], v[208:211], v[166:169], v[16:19]
	v_mfma_f32_16x16x32_bf16 v[56:59], v[200:203], v[176:179], v[56:59]
	v_mfma_f32_16x16x32_bf16 v[12:15], v[208:211], v[176:179], v[12:15]
	v_mfma_f32_16x16x32_bf16 v[52:55], v[200:203], v[184:187], v[52:55]
	v_mfma_f32_16x16x32_bf16 v[28:31], v[208:211], v[184:187], v[28:31]
	v_mfma_f32_16x16x32_bf16 v[48:51], v[200:203], v[192:195], v[48:51]
	v_mfma_f32_16x16x32_bf16 v[24:27], v[208:211], v[192:195], v[24:27]
	v_mfma_f32_16x16x32_bf16 v[60:63], v[204:207], v[172:175], v[60:63]
	v_mfma_f32_16x16x32_bf16 v[16:19], v[212:215], v[172:175], v[16:19]
	v_mfma_f32_16x16x32_bf16 v[56:59], v[204:207], v[180:183], v[56:59]
	v_mfma_f32_16x16x32_bf16 v[12:15], v[212:215], v[180:183], v[12:15]
	v_mfma_f32_16x16x32_bf16 v[52:55], v[204:207], v[188:191], v[52:55]
	v_mfma_f32_16x16x32_bf16 v[28:31], v[212:215], v[188:191], v[28:31]
	v_mfma_f32_16x16x32_bf16 v[48:51], v[204:207], v[196:199], v[48:51]
	v_mfma_f32_16x16x32_bf16 v[24:27], v[212:215], v[196:199], v[24:27]
	s_setprio 0
	s_mov_b32 m0, s84
	s_barrier
	ds_read_b128 v[166:169], v159 offset:49152
	ds_read_b128 v[172:175], v159 offset:50176
	ds_read_b128 v[176:179], v159 offset:51200
	ds_read_b128 v[180:183], v159 offset:52224
	ds_read_b128 v[184:187], v159 offset:53248
	ds_read_b128 v[188:191], v159 offset:54272
	ds_read_b128 v[192:195], v159 offset:55296
	ds_read_b128 v[196:199], v159 offset:56320
	s_add_u32 s98, s72, 0x80
	s_addc_u32 s99, s73, 0
	global_load_lds_dwordx4 v136, s[98:99]
	s_mov_b32 m0, s85
	s_nop 0
	global_load_lds_dwordx4 v140, s[98:99]
	s_barrier
	s_waitcnt lgkmcnt(0)
	s_setprio 1
	s_waitcnt lgkmcnt(0)
	v_mfma_f32_16x16x32_bf16 v[112:115], v[128:131], v[166:169], v[112:115]
	v_mfma_f32_16x16x32_bf16 v[88:91], v[148:151], v[166:169], v[88:91]
	v_mfma_f32_16x16x32_bf16 v[104:107], v[128:131], v[176:179], v[104:107]
	v_mfma_f32_16x16x32_bf16 v[80:83], v[148:151], v[176:179], v[80:83]
	v_mfma_f32_16x16x32_bf16 v[100:103], v[128:131], v[184:187], v[100:103]
	v_mfma_f32_16x16x32_bf16 v[64:67], v[148:151], v[184:187], v[64:67]
	v_mfma_f32_16x16x32_bf16 v[108:111], v[128:131], v[192:195], v[108:111]
	v_mfma_f32_16x16x32_bf16 v[68:71], v[148:151], v[192:195], v[68:71]
	v_mfma_f32_16x16x32_bf16 v[112:115], v[132:135], v[172:175], v[112:115]
	v_mfma_f32_16x16x32_bf16 v[88:91], v[162:165], v[172:175], v[88:91]
	v_mfma_f32_16x16x32_bf16 v[104:107], v[132:135], v[180:183], v[104:107]
	v_mfma_f32_16x16x32_bf16 v[80:83], v[162:165], v[180:183], v[80:83]
	v_mfma_f32_16x16x32_bf16 v[100:103], v[132:135], v[188:191], v[100:103]
	v_mfma_f32_16x16x32_bf16 v[64:67], v[162:165], v[188:191], v[64:67]
	v_mfma_f32_16x16x32_bf16 v[108:111], v[132:135], v[196:199], v[108:111]
	v_mfma_f32_16x16x32_bf16 v[68:71], v[162:165], v[196:199], v[68:71]
	s_setprio 0
	s_barrier
	s_add_u32 s12, s70, 0x40080
	s_addc_u32 s13, s71, 0
	s_add_i32 s52, s53, s78
	s_mov_b32 m0, s52
	s_nop 0
	global_load_lds_dwordx4 v138, s[12:13]
	s_add_i32 m0, s52, 0x2000
	s_nop 0
	global_load_lds_dwordx4 v142, s[12:13]
	s_waitcnt vmcnt(6)
	s_barrier
	s_setprio 1
	v_mfma_f32_16x16x32_bf16 v[44:47], v[200:203], v[166:169], v[44:47]
	v_mfma_f32_16x16x32_bf16 v[20:23], v[208:211], v[166:169], v[20:23]
	v_mfma_f32_16x16x32_bf16 v[40:43], v[200:203], v[176:179], v[40:43]
	v_mfma_f32_16x16x32_bf16 v[8:11], v[208:211], v[176:179], v[8:11]
	v_mfma_f32_16x16x32_bf16 v[36:39], v[200:203], v[184:187], v[36:39]
	v_mfma_f32_16x16x32_bf16 v[0:3], v[208:211], v[184:187], v[0:3]
	v_mfma_f32_16x16x32_bf16 v[32:35], v[200:203], v[192:195], v[32:35]
	v_mfma_f32_16x16x32_bf16 v[4:7], v[208:211], v[192:195], v[4:7]
	v_mfma_f32_16x16x32_bf16 v[44:47], v[204:207], v[172:175], v[44:47]
	v_mfma_f32_16x16x32_bf16 v[20:23], v[212:215], v[172:175], v[20:23]
	v_mfma_f32_16x16x32_bf16 v[40:43], v[204:207], v[180:183], v[40:43]
	v_mfma_f32_16x16x32_bf16 v[8:11], v[212:215], v[180:183], v[8:11]
	v_mfma_f32_16x16x32_bf16 v[36:39], v[204:207], v[188:191], v[36:39]
	v_mfma_f32_16x16x32_bf16 v[0:3], v[212:215], v[188:191], v[0:3]
	v_mfma_f32_16x16x32_bf16 v[32:35], v[204:207], v[196:199], v[32:35]
	v_mfma_f32_16x16x32_bf16 v[4:7], v[212:215], v[196:199], v[4:7]
	s_setprio 0
	s_add_i32 s49, s49, 2
	s_add_u32 s11, s11, 0x100
	s_addc_u32 s33, s33, 0
	s_cmp_gt_u32 s49, 13
	s_mov_b64 s[12:13], s[68:69]
	s_barrier
	s_cbranch_scc0 .LBB0_800
	v_lshl_or_b32 v150, s10, 7, v157
	v_add_u32_e32 v254, 0x2c00, v253
	global_load_dwordx4 v[208:211], v253, s[22:23] offset:16
	global_load_dwordx4 v[212:215], v253, s[24:25] offset:16
	global_load_dwordx4 v[216:219], v253, s[26:27] offset:16
	global_load_dwordx4 v[220:223], v253, s[36:37] offset:16
	v_cmp_gt_i32_e32 vcc, 15, v152
	s_mov_b64 s[70:71], -1
	s_and_saveexec_b64 s[68:69], vcc
	s_cbranch_execz .LBB0_805
	v_cmp_eq_u32_e32 vcc, 0, v152
	v_cmp_ne_u32_e64 s[12:13], 0, v152
	s_and_saveexec_b64 s[70:71], s[12:13]
	v_ashrrev_i32_e32 v151, 31, v150
	v_mov_b64_e32 v[148:149], v[150:151]
	s_or_b64 exec, exec, s[70:71]
	s_orn2_b64 s[70:71], vcc, exec
